# scan: static s_setprio 1 for the PRODUCER waves 0-3 (they are the per-step bottleneck per barrier-wait timing); consumers stage-1 read prefetch kept
# baseline (speedup 1.0000x reference)
.LBB0_396:
	s_and_b64 vcc, exec, s[0:1]
	s_cbranch_vccz .LBB0_408
	s_setprio 1
	s_lshl_b32 s0, s2, 19
	s_and_b32 s71, s0, 0x3c00000
	s_lshl_b32 s0, s75, 13
	s_and_b32 s70, s2, 1
	s_or_b32 s68, s0, s71
	v_readlane_b32 s0, v255, 37
	s_add_u32 s0, s0, s68
	v_readlane_b32 s1, v255, 38
	s_addc_u32 s1, s1, 0
	s_lshl_b32 s69, s33, 8
	s_add_u32 s0, s0, s69
	s_addc_u32 s1, s1, 0
	v_readlane_b32 s72, v255, 32
	s_add_u32 s68, s72, s68
	v_readlane_b32 s72, v255, 31
	s_addc_u32 s72, s72, 0
	s_add_u32 s68, s68, s69
	s_addc_u32 s69, s72, 0
	v_lshl_add_u64 v[10:11], s[0:1], 0, v[66:67]
	s_mov_b64 s[0:1], 0x3f8000
	v_lshl_add_u64 v[12:13], s[68:69], 0, v[66:67]
	v_lshl_add_u64 v[2:3], v[10:11], 0, s[0:1]
	v_lshl_add_u64 v[4:5], v[12:13], 0, s[0:1]
	s_mov_b32 s0, 0x3f9000
	s_waitcnt vmcnt(0)
	v_add_co_u32_e32 v6, vcc, s0, v10
	s_lshl_b32 s72, s33, 20
	s_nop 0
	v_addc_co_u32_e32 v7, vcc, 0, v11, vcc
	v_add_co_u32_e32 v8, vcc, s0, v12
	s_lshl_b32 s70, s70, 19
	s_nop 0
	v_addc_co_u32_e32 v9, vcc, 0, v13, vcc
	global_load_dword v54, v[2:3], off offset:1024
	global_load_dword v52, v[4:5], off offset:1024
	global_load_dword v56, v[2:3], off offset:2048
	global_load_dword v53, v[4:5], off offset:2048
	global_load_dword v55, v[4:5], off offset:3072
	global_load_dword v58, v[2:3], off offset:3072
	global_load_dword v51, v[8:9], off offset:-4096
	global_load_dword v57, v[8:9], off
	global_load_dword v62, v[6:7], off offset:1024
	global_load_dword v59, v[8:9], off offset:1024
	global_load_dword v64, v[6:7], off offset:2048
	global_load_dword v61, v[8:9], off offset:2048
	global_load_dword v63, v[8:9], off offset:3072
	global_load_dword v65, v[6:7], off offset:3072
	s_or_b32 s70, s72, s70
	s_or_b32 s70, s70, s71
	v_readlane_b32 s0, v255, 34
	v_readlane_b32 s1, v255, 35
	s_add_u32 s0, s0, s70
	s_addc_u32 s1, s1, 0
	v_lshl_add_u64 v[14:15], s[0:1], 0, v[70:71]
	s_movk_i32 s0, 0x1000
	v_add_co_u32_e32 v8, vcc, s0, v14
	s_mov_b64 s[0:1], 0x3f0000
	s_nop 0
	v_addc_co_u32_e32 v9, vcc, 0, v15, vcc
	v_lshl_add_u64 v[2:3], v[10:11], 0, s[0:1]
	v_lshl_add_u64 v[4:5], v[12:13], 0, s[0:1]
	s_mov_b32 s0, 0x3f1000
	v_add_co_u32_e32 v16, vcc, s0, v10
	s_lshl_b32 s88, s75, 9
	s_nop 0
	v_addc_co_u32_e32 v17, vcc, 0, v11, vcc
	v_add_co_u32_e32 v18, vcc, s0, v12
	s_lshl_b32 s0, s75, 4
	s_nop 0
	v_addc_co_u32_e32 v19, vcc, 0, v13, vcc
	global_load_dword v60, v[6:7], off offset:-4096
	global_load_dword v80, v[6:7], off
	global_load_dword v39, v[2:3], off offset:1024
	global_load_dword v36, v[4:5], off offset:1024
	global_load_dword v41, v[2:3], off offset:2048
	global_load_dword v38, v[4:5], off offset:2048
	global_load_dword v40, v[4:5], off offset:3072
	global_load_dword v42, v[2:3], off offset:3072
	global_load_dword v37, v[16:17], off offset:-4096
	global_load_dword v35, v[18:19], off offset:-4096
	global_load_dword v45, v[16:17], off
	global_load_dword v43, v[18:19], off
	global_load_dword v46, v[16:17], off offset:1024
	global_load_dword v44, v[18:19], off offset:1024
	global_load_dword v48, v[16:17], off offset:2048
	global_load_dword v50, v[16:17], off offset:3072
	global_load_dword v47, v[18:19], off offset:2048
	global_load_dword v49, v[18:19], off offset:3072
	global_load_dwordx4 v[2:5], v[8:9], off offset:4032
	s_nop 0
	global_load_dwordx4 v[6:9], v[8:9], off offset:3968
	s_cmp_lt_u32 s74, 64
	s_cselect_b64 s[68:69], -1, 0
	s_cmpk_lt_u32 s74, 0x80
	s_mulk_i32 s75, 0x220
	s_cselect_b64 s[70:71], -1, 0
	s_cmpk_lt_u32 s74, 0xc0
	v_add_u32_e32 v18, s75, v158
	s_mov_b32 s87, 0
	v_add_u32_e32 v16, s0, v102
	v_add_u32_e32 v17, s0, v103
	s_cselect_b64 s[72:73], -1, 0
	v_lshl_add_u32 v18, v18, 2, 0
	s_movk_i32 s0, 0x7c
	s_waitcnt vmcnt(33)
	v_mov_b32_e32 v24, v54
	s_waitcnt vmcnt(32)
	v_mov_b32_e32 v20, v52
	s_waitcnt vmcnt(31)
	v_mov_b32_e32 v25, v56
	s_waitcnt vmcnt(30)
	v_mov_b32_e32 v21, v53
	s_waitcnt vmcnt(29)
	v_mov_b32_e32 v23, v55
	s_waitcnt vmcnt(28)
	v_mov_b32_e32 v26, v58
	s_waitcnt vmcnt(27)
	v_mov_b32_e32 v19, v51
	s_waitcnt vmcnt(26)
	v_mov_b32_e32 v27, v57
	s_waitcnt vmcnt(25)
	v_mov_b32_e32 v32, v62
	s_waitcnt vmcnt(24)
	v_mov_b32_e32 v28, v59
	s_waitcnt vmcnt(23)
	v_mov_b32_e32 v33, v64
	s_waitcnt vmcnt(22)
	v_mov_b32_e32 v30, v61
	s_waitcnt vmcnt(21)
	v_mov_b32_e32 v31, v63
	s_waitcnt vmcnt(20)
	v_mov_b32_e32 v34, v65
	s_waitcnt vmcnt(19)
	v_mov_b32_e32 v22, v60
	s_waitcnt vmcnt(18)
	v_mov_b32_e32 v29, v80
	s_branch .LBB0_399

.LBB0_427:
	s_and_b64 vcc, exec, s[68:69]
	s_cbranch_vccz .LBB0_374
	s_setprio 1
	s_lshl_b32 s72, s94, 22
	s_lshl_b32 s1, s33, 20
	s_lshl_b32 s0, s0, 10
	s_lshl_b32 s75, s87, 13
	s_and_b32 s70, s2, 1
	s_or_b32 s73, s72, s1
	s_and_b32 s74, s89, 3
	s_or_b32 s68, s75, s0
	v_readlane_b32 s0, v255, 39
	s_add_u32 s0, s0, s68
	v_readlane_b32 s1, v255, 40
	s_addc_u32 s1, s1, 0
	s_lshl_b32 s33, s33, 8
	s_add_u32 s0, s0, s33
	s_addc_u32 s1, s1, 0
	v_readlane_b32 s69, v255, 32
	s_add_u32 s68, s69, s68
	v_readlane_b32 s69, v255, 31
	s_addc_u32 s69, s69, 0
	s_add_u32 s68, s68, s33
	v_lshl_add_u64 v[2:3], s[0:1], 0, v[66:67]
	s_movk_i32 s0, 0x1000
	s_addc_u32 s69, s69, 0
	s_waitcnt vmcnt(0)
	v_add_co_u32_e32 v6, vcc, s0, v2
	v_lshl_add_u64 v[4:5], s[68:69], 0, v[66:67]
	s_nop 0
	v_addc_co_u32_e32 v7, vcc, 0, v3, vcc
	v_add_co_u32_e32 v8, vcc, s0, v4
	s_mov_b64 s[0:1], 0x8000
	s_nop 0
	v_addc_co_u32_e32 v9, vcc, 0, v5, vcc
	global_load_dword v105, v[2:3], off
	global_load_dword v64, v[4:5], off
	global_load_dword v81, v[2:3], off offset:1024
	global_load_dword v61, v[4:5], off offset:1024
	global_load_dword v65, v[2:3], off offset:2048
	global_load_dword v57, v[4:5], off offset:2048
	global_load_dword v55, v[4:5], off offset:3072
	global_load_dword v62, v[2:3], off offset:3072
	global_load_dword v80, v[6:7], off
	global_load_dword v59, v[8:9], off
	global_load_dword v63, v[6:7], off offset:1024
	global_load_dword v56, v[8:9], off offset:1024
	global_load_dword v60, v[6:7], off offset:2048
	global_load_dword v54, v[8:9], off offset:2048
	global_load_dword v53, v[8:9], off offset:3072
	global_load_dword v58, v[6:7], off offset:3072
	v_lshl_add_u64 v[8:9], v[2:3], 0, s[0:1]
	v_lshl_add_u64 v[10:11], v[4:5], 0, s[0:1]
	s_mov_b32 s0, 0x9000
	v_add_co_u32_e32 v2, vcc, s0, v2
	s_lshl_b32 s33, s70, 19
	s_nop 0
	v_addc_co_u32_e32 v3, vcc, 0, v3, vcc
	s_or_b32 s70, s73, s33
	s_mov_b32 s71, s96
	v_add_co_u32_e32 v4, vcc, s0, v4
	v_lshl_add_u64 v[6:7], v[74:75], 0, s[70:71]
	s_nop 0
	v_addc_co_u32_e32 v5, vcc, 0, v5, vcc
	global_load_dword v51, v[2:3], off offset:-4096
	global_load_dword v50, v[8:9], off offset:1024
	global_load_dword v47, v[10:11], off offset:1024
	global_load_dword v49, v[8:9], off offset:2048
	global_load_dword v45, v[10:11], off offset:2048
	global_load_dword v46, v[2:3], off
	global_load_dword v43, v[10:11], off offset:3072
	global_load_dword v48, v[8:9], off offset:3072
	global_load_dword v52, v[4:5], off offset:-4096
	global_load_dword v41, v[4:5], off
	global_load_dword v44, v[2:3], off offset:1024
	global_load_dword v39, v[4:5], off offset:1024
	global_load_dword v42, v[2:3], off offset:2048
	global_load_dword v38, v[4:5], off offset:2048
	global_load_dword v37, v[4:5], off offset:3072
	global_load_dword v40, v[2:3], off offset:3072
	s_nop 0
	global_load_dwordx4 v[2:5], v[6:7], off
	s_nop 0
	global_load_dwordx4 v[6:9], v[6:7], off offset:64
	s_lshl_b32 s86, s87, 9
	s_lshl_b32 s68, s87, 4
	s_cmp_lt_u32 s88, 64
	s_cselect_b64 s[0:1], -1, 0
	s_cmpk_gt_u32 s88, 0x7f
	s_mulk_i32 s87, 0x220
	v_lshlrev_b32_e32 v10, 19, v68
	v_add_u32_e32 v18, s68, v102
	v_add_u32_e32 v19, s68, v103
	s_cselect_b64 s[68:69], -1, 0
	s_cmpk_gt_u32 s88, 0xbf
	v_add_u32_e32 v12, s87, v158
	v_or_b32_e32 v68, s73, v10
	s_cselect_b64 s[70:71], -1, 0
	v_lshl_add_u32 v20, v12, 2, 0
	v_lshl_or_b32 v12, s74, 8, v66
	s_add_i32 s72, s72, s75
	v_lshl_add_u64 v[10:11], v[70:71], 0, v[68:69]
	s_mov_b32 s33, 0
	v_or_b32_e32 v12, s72, v12
	v_mov_b32_e32 v13, v67
	s_waitcnt vmcnt(33)
	v_mov_b32_e32 v23, v105
	s_waitcnt vmcnt(32)
	v_mov_b32_e32 v21, v64
	s_waitcnt vmcnt(24)
	v_mov_b32_e32 v29, v59
	v_mov_b32_e32 v22, v61
	s_waitcnt vmcnt(22)
	v_mov_b32_e32 v30, v56
	v_mov_b32_e32 v24, v57
	v_mov_b32_e32 v25, v55
	s_waitcnt vmcnt(20)
	v_mov_b32_e32 v32, v54
	s_waitcnt vmcnt(19)
	v_mov_b32_e32 v33, v53
	v_mov_b32_e32 v26, v81
	v_mov_b32_e32 v27, v65
	v_mov_b32_e32 v28, v62
	v_mov_b32_e32 v31, v80
	v_mov_b32_e32 v34, v63
	v_mov_b32_e32 v35, v60
	s_waitcnt vmcnt(18)
	v_mov_b32_e32 v36, v58
	s_branch .LBB0_430
